# S5 pass B: L2 touch of the sample-step SSM state words one block ahead (hint loads)
# baseline (speedup 1.0000x reference)
; __device__ __forceinline__ int opq(int v) { asm volatile("" : "+v"(v)); return v; }
; __global__ void __launch_bounds__(512, 2) mk_fwd(Args a) {
;     ...
;                 for (int blk = 0; blk < SEGB; ++blk) { u32x4 cur[2] = {pre[0], pre[1]};
;                     if (blk + 1 < SEGB) ssm_stage_load(a, r0 + (blk + 1) * SBLK, SBLK, gq, pre);
;                     ssm_unit<true>(a, lds, T, cur, l, r0 + blk * SBLK, SBLK, gq, hr, hi, wave); }
;                 if (seg == NSEG - 1) { const size_t so = ((size_t)l * NBATCH + b) * NG * NP + g * NP + lane; a.out[O_HRP + so] = hr; a.out[O_HIP + so] = hi; } }
;             for (int v = bx; v < DEC_B * 4; v += G) { const int gq = v & 3, b = v >> 2; const int lane = opq(threadIdx.x) & 63, g = gq * 8 + wave;
;                 const size_t so = ((size_t)l * DEC_B + b) * NG * NP + g * NP + lane;
;                 ssm_stage_load(a, (size_t)NTOK_P + b * DEC_T, DEC_T, gq, pre);
;                 float hr = a.in[I_SR][so], hi = a.in[I_SI][so];
;                 ssm_unit<true>(a, lds, T, pre, l, (size_t)NTOK_P + b * DEC_T, DEC_T, gq, hr, hi, wave);
;                 a.out[O_HRS + so] = hr; a.out[O_HIS + so] = hi; } }
.LBB0_472:
	s_add_u32 s6, s6, 0x10000
	s_addc_u32 s7, s7, 0
	s_cmp_eq_u32 s12, 3
	s_cbranch_scc0 .Lssp_skip
	v_readlane_b32 s98, v255, 41
	s_and_b32 s99, s2, 0xff
	s_lshl_b32 s98, s98, 18
	s_lshr_b32 s100, s99, 2
	s_and_b32 s99, s99, 3
	s_lshl_b32 s100, s100, 11
	s_lshl_b32 s99, s99, 9
	s_add_i32 s98, s98, s100
	s_add_i32 s98, s98, s99
	v_add_u32_e32 v236, s98, v184
	v_lshlrev_b32_e32 v236, 2, v236
	v_mov_b32_e32 v237, 0
	v_readlane_b32 s98, v252, 8
	v_readlane_b32 s99, v252, 9
	v_readlane_b32 s100, v252, 10
	v_readlane_b32 s101, v252, 11
	v_lshl_add_u64 v[238:239], s[98:99], 0, v[236:237]
	v_lshl_add_u64 v[240:241], s[100:101], 0, v[236:237]
	global_load_dword v242, v[238:239], off
	global_load_dword v243, v[240:241], off
	v_add_u32_e32 v236, 0x80000, v236
	v_lshl_add_u64 v[238:239], s[98:99], 0, v[236:237]
	v_lshl_add_u64 v[240:241], s[100:101], 0, v[236:237]
	global_load_dword v244, v[238:239], off
	global_load_dword v245, v[240:241], off
.Lssp_skip:
	s_cmp_eq_u32 s12, 4
	s_barrier
	s_cbranch_scc0 .LBB0_458
	s_cmp_eq_u32 s72, 7
	s_cbranch_scc0 .LBB0_475
	s_lshl_b32 s26, s35, 6
	s_lshl_b64 s[0:1], s[54:55], 2
	s_add_u32 s6, s22, s0
	s_addc_u32 s7, s23, s1
	s_lshl_b64 s[0:1], s[26:27], 2
	s_add_u32 s0, s6, s0
	s_addc_u32 s1, s7, s1
	v_lshlrev_b32_e32 v0, 2, v93
	v_lshl_add_u64 v[12:13], s[0:1], 0, v[0:1]
	v_add_co_u32_e32 v14, vcc, 0x4400000, v12
	s_nop 1
	v_addc_co_u32_e32 v15, vcc, 0, v13, vcc
	v_add_co_u32_e32 v12, vcc, 0x4420000, v12
	global_store_dword v[14:15], v82, off
	s_nop 0
	v_addc_co_u32_e32 v13, vcc, 0, v13, vcc
	global_store_dword v[12:13], v83, off
